# v19 + attention output stores paired via v_permlane32_swap into 8 dwordx4 per lane instead of 16 dwordx2 (strategy: widen epilogue stores)
# speedup vs baseline: 1.0230x; 1.0066x over previous
; template <int NQG>
; DI void store_o(const f16v (&O)[2][NQG], half_t* orow0  , int lane) {
;   const int r = lane & 31, h = lane >> 5;
; #pragma unroll
;   for (int qg = 0; qg < NQG; ++qg)
; #pragma unroll
;     for (int dvt = 0; dvt < 2; ++dvt)
; #pragma unroll
;       for (int c = 0; c < 4; ++c) {
;         h4 o;
; #pragma unroll
;         for (int j = 0; j < 4; ++j) o[j] = (half_t)O[dvt][qg][4 * c + j];
;         *(h4*)(orow0 + (size_t)(qg * 32 + r) * 1024 + dvt * 32 + 8 * c + 4 * h) = o;
;       }
; }
.LBB0_2076:
	s_and_b64 vcc, exec, s[8:9]
	s_cbranch_vccz .LBB0_1905
	v_mov_b32_e32 v183, v0
	s_waitcnt lgkmcnt(0)
	v_lshl_add_u64 v[2:3], s[6:7], 0, v[182:183]
	v_mov_b32_e32 v187, v0
	v_lshl_add_u64 v[4:5], v[2:3], 0, v[186:187]
	v_cvt_pk_f16_f32 v33, v140, v141
	v_cvt_pk_f16_f32 v32, v142, v143
	v_mbcnt_lo_u32_b32 v28, -1, 0
	v_mbcnt_hi_u32_b32 v28, -1, v28
	v_lshrrev_b32_e32 v28, 5, v28
	v_lshlrev_b32_e32 v28, 3, v28
	v_mov_b32_e32 v29, 0
	v_lshl_add_u64 v[30:31], v[4:5], 0, v[28:29]
	s_waitcnt vmcnt(1)
	v_cvt_pk_f16_f32 v35, v132, v133
	v_cvt_pk_f16_f32 v34, v136, v137
	s_nop 1
	v_permlane32_swap_b32_e32 v32, v34
	v_permlane32_swap_b32_e32 v33, v35
	global_store_dwordx4 v[30:31], v[32:35], off
	v_cvt_pk_f16_f32 v37, v128, v129
	v_cvt_pk_f16_f32 v36, v130, v131
	v_cvt_pk_f16_f32 v39, v124, v125
	v_cvt_pk_f16_f32 v38, v126, v127
	s_nop 1
	v_permlane32_swap_b32_e32 v36, v38
	v_permlane32_swap_b32_e32 v37, v39
	global_store_dwordx4 v[30:31], v[36:39], off offset:32
	v_cvt_pk_f16_f32 v41, v120, v121
	v_cvt_pk_f16_f32 v40, v122, v123
	v_cvt_pk_f16_f32 v43, v112, v113
	v_cvt_pk_f16_f32 v42, v114, v115
	s_nop 1
	v_permlane32_swap_b32_e32 v40, v42
	v_permlane32_swap_b32_e32 v41, v43
	global_store_dwordx4 v[30:31], v[40:43], off offset:64
	v_cvt_pk_f16_f32 v45, v104, v105
	v_cvt_pk_f16_f32 v44, v106, v107
	v_cvt_pk_f16_f32 v47, v96, v97
	v_cvt_pk_f16_f32 v46, v98, v99
	v_mov_b32_e32 v189, v0
	s_nop 1
	v_permlane32_swap_b32_e32 v44, v46
	v_permlane32_swap_b32_e32 v45, v47
	global_store_dwordx4 v[30:31], v[44:47], off offset:96
	v_lshl_add_u64 v[2:3], v[2:3], 0, v[188:189]
	v_cvt_pk_f16_f32 v33, v134, v135
	v_cvt_pk_f16_f32 v32, v138, v139
	v_mbcnt_lo_u32_b32 v28, -1, 0
	v_mbcnt_hi_u32_b32 v28, -1, v28
	v_lshrrev_b32_e32 v28, 5, v28
	v_lshlrev_b32_e32 v28, 3, v28
	v_mov_b32_e32 v29, 0
	v_lshl_add_u64 v[48:49], v[2:3], 0, v[28:29]
	v_cvt_pk_f16_f32 v35, v116, v117
	v_cvt_pk_f16_f32 v34, v118, v119
	s_nop 1
	v_permlane32_swap_b32_e32 v32, v34
	v_permlane32_swap_b32_e32 v33, v35
	global_store_dwordx4 v[48:49], v[32:35], off
	v_cvt_pk_f16_f32 v37, v108, v109
	v_cvt_pk_f16_f32 v36, v110, v111
	v_cvt_pk_f16_f32 v39, v100, v101
	v_cvt_pk_f16_f32 v38, v102, v103
	s_nop 1
	v_permlane32_swap_b32_e32 v36, v38
	v_permlane32_swap_b32_e32 v37, v39
	global_store_dwordx4 v[48:49], v[36:39], off offset:32
	v_cvt_pk_f16_f32 v41, v92, v93
	v_cvt_pk_f16_f32 v40, v94, v95
	v_cvt_pk_f16_f32 v43, v88, v89
	v_cvt_pk_f16_f32 v42, v90, v91
	s_nop 1
	v_permlane32_swap_b32_e32 v40, v42
	v_permlane32_swap_b32_e32 v41, v43
	global_store_dwordx4 v[48:49], v[40:43], off offset:64
	v_cvt_pk_f16_f32 v45, v84, v85
	v_cvt_pk_f16_f32 v44, v86, v87
	v_cvt_pk_f16_f32 v47, v80, v81
	v_cvt_pk_f16_f32 v46, v82, v83
	s_nop 1
	v_permlane32_swap_b32_e32 v44, v46
	v_permlane32_swap_b32_e32 v45, v47
	global_store_dwordx4 v[48:49], v[44:47], off offset:96
	s_branch .LBB0_1905

; template <int NQG>
; DI void store_o(const f16v (&O)[2][NQG], half_t* orow0  , int lane) {
;   const int r = lane & 31, h = lane >> 5;
; #pragma unroll
;   for (int qg = 0; qg < NQG; ++qg)
; #pragma unroll
;     for (int dvt = 0; dvt < 2; ++dvt)
; #pragma unroll
;       for (int c = 0; c < 4; ++c) {
;         h4 o;
; #pragma unroll
;         for (int j = 0; j < 4; ++j) o[j] = (half_t)O[dvt][qg][4 * c + j];
;         *(h4*)(orow0 + (size_t)(qg * 32 + r) * 1024 + dvt * 32 + 8 * c + 4 * h) = o;
;       }
; }
.LBB0_2211:
	v_mov_b32_e32 v199, v0
	s_waitcnt lgkmcnt(0)
	v_lshl_add_u64 v[2:3], s[16:17], 0, v[198:199]
	v_mov_b32_e32 v201, v0
	v_lshl_add_u64 v[4:5], v[2:3], 0, v[200:201]
	v_cvt_pk_f16_f32 v33, v140, v141
	v_cvt_pk_f16_f32 v32, v142, v143
	v_mbcnt_lo_u32_b32 v28, -1, 0
	v_mbcnt_hi_u32_b32 v28, -1, v28
	v_lshrrev_b32_e32 v28, 5, v28
	v_lshlrev_b32_e32 v28, 3, v28
	v_mov_b32_e32 v29, 0
	v_lshl_add_u64 v[30:31], v[4:5], 0, v[28:29]
	s_waitcnt vmcnt(1)
	v_cvt_pk_f16_f32 v35, v136, v137
	v_cvt_pk_f16_f32 v34, v138, v139
	s_nop 1
	v_permlane32_swap_b32_e32 v32, v34
	v_permlane32_swap_b32_e32 v33, v35
	global_store_dwordx4 v[30:31], v[32:35], off
	v_cvt_pk_f16_f32 v37, v132, v133
	v_cvt_pk_f16_f32 v36, v134, v135
	v_cvt_pk_f16_f32 v39, v128, v129
	v_cvt_pk_f16_f32 v38, v130, v131
	s_nop 1
	v_permlane32_swap_b32_e32 v36, v38
	v_permlane32_swap_b32_e32 v37, v39
	global_store_dwordx4 v[30:31], v[36:39], off offset:32
	v_cvt_pk_f16_f32 v41, v124, v125
	v_cvt_pk_f16_f32 v40, v126, v127
	v_cvt_pk_f16_f32 v43, v120, v121
	v_cvt_pk_f16_f32 v42, v122, v123
	s_nop 1
	v_permlane32_swap_b32_e32 v40, v42
	v_permlane32_swap_b32_e32 v41, v43
	global_store_dwordx4 v[30:31], v[40:43], off offset:64
	v_cvt_pk_f16_f32 v45, v116, v117
	v_cvt_pk_f16_f32 v44, v118, v119
	v_cvt_pk_f16_f32 v47, v112, v113
	v_cvt_pk_f16_f32 v46, v114, v115
	v_mov_b32_e32 v203, v0
	s_nop 1
	v_permlane32_swap_b32_e32 v44, v46
	v_permlane32_swap_b32_e32 v45, v47
	global_store_dwordx4 v[30:31], v[44:47], off offset:96
	v_lshl_add_u64 v[2:3], v[2:3], 0, v[202:203]
	v_cvt_pk_f16_f32 v33, v108, v109
	v_cvt_pk_f16_f32 v32, v110, v111
	v_mbcnt_lo_u32_b32 v28, -1, 0
	v_mbcnt_hi_u32_b32 v28, -1, v28
	v_lshrrev_b32_e32 v28, 5, v28
	v_lshlrev_b32_e32 v28, 3, v28
	v_mov_b32_e32 v29, 0
	v_lshl_add_u64 v[48:49], v[2:3], 0, v[28:29]
	v_cvt_pk_f16_f32 v35, v104, v105
	v_cvt_pk_f16_f32 v34, v106, v107
	s_nop 1
	v_permlane32_swap_b32_e32 v32, v34
	v_permlane32_swap_b32_e32 v33, v35
	global_store_dwordx4 v[48:49], v[32:35], off
	v_cvt_pk_f16_f32 v37, v100, v101
	v_cvt_pk_f16_f32 v36, v102, v103
	v_cvt_pk_f16_f32 v39, v96, v97
	v_cvt_pk_f16_f32 v38, v98, v99
	s_nop 1
	v_permlane32_swap_b32_e32 v36, v38
	v_permlane32_swap_b32_e32 v37, v39
	global_store_dwordx4 v[48:49], v[36:39], off offset:32
	v_cvt_pk_f16_f32 v41, v92, v93
	v_cvt_pk_f16_f32 v40, v94, v95
	v_cvt_pk_f16_f32 v43, v88, v89
	v_cvt_pk_f16_f32 v42, v90, v91
	s_nop 1
	v_permlane32_swap_b32_e32 v40, v42
	v_permlane32_swap_b32_e32 v41, v43
	global_store_dwordx4 v[48:49], v[40:43], off offset:64
	v_cvt_pk_f16_f32 v45, v84, v85
	v_cvt_pk_f16_f32 v44, v86, v87
	v_cvt_pk_f16_f32 v47, v80, v81
	v_cvt_pk_f16_f32 v46, v82, v83
	s_nop 1
	v_permlane32_swap_b32_e32 v44, v46
	v_permlane32_swap_b32_e32 v45, v47
	global_store_dwordx4 v[48:49], v[44:47], off offset:96
	s_branch .LBB0_2080
